# t15 + P5 PV waves: V DMAs packed one per MFMA at the start of the step (2 in the head, 6 behind MFMAs 1..6)
# baseline (speedup 1.0000x reference)
; #define SBAR() __builtin_amdgcn_sched_barrier(0)
; #define RS_BAR() do { asm volatile("s_waitcnt lgkmcnt(0)" ::: "memory"); __builtin_amdgcn_s_barrier(); asm volatile("" ::: "memory"); } while (0)
; #define VM0() asm volatile("s_waitcnt vmcnt(0)" ::: "memory")
; #define VM0() asm volatile("s_waitcnt vmcnt(0)" ::: "memory")
; #define VMMA(OD, F) do { OD = __builtin_amdgcn_mfma_f32_32x32x16_bf16(pa0, PKF(F[0], F[1]), OD, 0, 0, 0); OD = __builtin_amdgcn_mfma_f32_32x32x16_bf16(pa1, PKF(F[2], F[3]), OD, 0, 0, 0); \
;       OD = __builtin_amdgcn_mfma_f32_32x32x16_bf16(pa2, PKF(F[4], F[5]), OD, 0, 0, 0); OD = __builtin_amdgcn_mfma_f32_32x32x16_bf16(pa3, PKF(F[6], F[7]), OD, 0, 0, 0); } while (0)
; #define LW(n) do { asm volatile("s_waitcnt lgkmcnt(" #n ")" ::: "memory"); SBAR(); } while (0)
; template <class Epi>
; __device__ __forceinline__ void attn_rs_body(const bf16* __restrict__ Qb, const bf16* __restrict__ Kc, const bf16* __restrict__ V0c, const bf16* __restrict__ V1c, int NT, char* lds, const Epi& epi) {
;     ...
;       const int vb = vb0 + b * 32768;
;       s16x4 fa[8], fb[8];
;       { const int tv = j < NT ? j : NT - 1; VDMA(tv, b ^ 1); }
;       asm volatile("s_waitcnt lgkmcnt(0)" ::: "memory"); SBAR();
;       VRD(fa, 0, 0); VRD(fb, 1, 0); LW(8); VMMA(o[0], fa);
;       VRD(fa, 2, 0); LW(8); VMMA(o[1], fb);
;       VRD(fb, 3, 0); LW(8); VMMA(o[2], fa);
;       VRD(fa, 0, 1); LW(8); VMMA(o[3], fb);
;       VRD(fb, 1, 1); LW(8); VMMA(o[4], fa);
;       VRD(fa, 2, 1); LW(8); VMMA(o[5], fb);
;       VRD(fb, 3, 1); LW(8); VMMA(o[6], fa);
;       LW(0); VMMA(o[7], fb);
;       VM0(); RS_BAR();
;     }
.LBB0_500:
	s_lshl_b32 s72, s72, 15
	v_lshl_add_u64 v[244:245], v[176:177], 0, s[48:49]
	s_add_i32 s72, s51, s72
	v_lshl_add_u64 v[246:247], v[174:175], 0, s[48:49]
	v_lshl_add_u32 v0, s71, 15, v182
	s_waitcnt lgkmcnt(0)
	ds_read_b64_tr_b16 v[146:147], v0 offset:0
	ds_read_b64_tr_b16 v[148:149], v0 offset:0x800
	ds_read_b64_tr_b16 v[150:151], v0 offset:0x1000
	ds_read_b64_tr_b16 v[152:153], v0 offset:0x1800
	ds_read_b64_tr_b16 v[154:155], v0 offset:0x2000
	ds_read_b64_tr_b16 v[156:157], v0 offset:0x2800
	ds_read_b64_tr_b16 v[158:159], v0 offset:0x3000
	ds_read_b64_tr_b16 v[160:161], v0 offset:0x3800
	ds_read_b64_tr_b16 v[184:185], v0 offset:0x200
	ds_read_b64_tr_b16 v[186:187], v0 offset:0xa00
	ds_read_b64_tr_b16 v[188:189], v0 offset:0x1200
	ds_read_b64_tr_b16 v[190:191], v0 offset:0x1a00
	ds_read_b64_tr_b16 v[192:193], v0 offset:0x2200
	ds_read_b64_tr_b16 v[194:195], v0 offset:0x2a00
	ds_read_b64_tr_b16 v[196:197], v0 offset:0x3200
	ds_read_b64_tr_b16 v[198:199], v0 offset:0x3a00
	s_add_i32 m0, s72, 0x8000
	v_lshl_add_u64 v[248:249], v[244:245], 0, s[12:13]
	global_load_lds_dwordx4 v[248:249], off
	s_add_i32 m0, s72, 0xc000
	v_lshl_add_u64 v[250:251], v[244:245], 0, s[14:15]
	global_load_lds_dwordx4 v[250:251], off
	s_waitcnt lgkmcnt(8)
	s_nop 0
	v_mfma_f32_32x32x16_bf16 v[114:129], v[142:145], v[146:149], v[114:129]
	ds_read_b64_tr_b16 v[146:147], v0 offset:0x400
	ds_read_b64_tr_b16 v[148:149], v0 offset:0xc00
	s_add_i32 m0, s72, 0x8400
	v_lshl_add_u64 v[248:249], v[244:245], 0, s[16:17]
	global_load_lds_dwordx4 v[248:249], off
	v_mfma_f32_32x32x16_bf16 v[114:129], v[138:141], v[150:153], v[114:129]
	ds_read_b64_tr_b16 v[150:151], v0 offset:0x1400
	ds_read_b64_tr_b16 v[152:153], v0 offset:0x1c00
	s_add_i32 m0, s72, 0xc400
	v_lshl_add_u64 v[250:251], v[244:245], 0, s[18:19]
	global_load_lds_dwordx4 v[250:251], off
	v_mfma_f32_32x32x16_bf16 v[114:129], v[134:137], v[154:157], v[114:129]
	ds_read_b64_tr_b16 v[154:155], v0 offset:0x2400
	ds_read_b64_tr_b16 v[156:157], v0 offset:0x2c00
	s_add_i32 m0, s72, 0x8800
	v_lshl_add_u64 v[248:249], v[246:247], 0, s[12:13]
	global_load_lds_dwordx4 v[248:249], off
	v_mfma_f32_32x32x16_bf16 v[114:129], v[130:133], v[158:161], v[114:129]
	ds_read_b64_tr_b16 v[158:159], v0 offset:0x3400
	ds_read_b64_tr_b16 v[160:161], v0 offset:0x3c00
	s_waitcnt lgkmcnt(8)
	s_add_i32 m0, s72, 0xc800
	v_lshl_add_u64 v[250:251], v[246:247], 0, s[14:15]
	global_load_lds_dwordx4 v[250:251], off
	v_mfma_f32_32x32x16_bf16 v[98:113], v[142:145], v[184:187], v[98:113]
	ds_read_b64_tr_b16 v[184:185], v0 offset:0x600
	ds_read_b64_tr_b16 v[186:187], v0 offset:0xe00
	s_add_i32 m0, s72, 0x8c00
	v_lshl_add_u64 v[248:249], v[246:247], 0, s[16:17]
	global_load_lds_dwordx4 v[248:249], off
	v_mfma_f32_32x32x16_bf16 v[98:113], v[138:141], v[188:191], v[98:113]
	ds_read_b64_tr_b16 v[188:189], v0 offset:0x1600
	ds_read_b64_tr_b16 v[190:191], v0 offset:0x1e00
	s_add_i32 m0, s72, 0xcc00
	v_lshl_add_u64 v[250:251], v[246:247], 0, s[18:19]
	global_load_lds_dwordx4 v[250:251], off
	v_mfma_f32_32x32x16_bf16 v[98:113], v[134:137], v[192:195], v[98:113]
	ds_read_b64_tr_b16 v[192:193], v0 offset:0x2600
	ds_read_b64_tr_b16 v[194:195], v0 offset:0x2e00
	v_mfma_f32_32x32x16_bf16 v[98:113], v[130:133], v[196:199], v[98:113]
	ds_read_b64_tr_b16 v[196:197], v0 offset:0x3600
	ds_read_b64_tr_b16 v[198:199], v0 offset:0x3e00
	s_waitcnt lgkmcnt(8)
	v_mfma_f32_32x32x16_bf16 v[82:97], v[142:145], v[146:149], v[82:97]
	ds_read_b64_tr_b16 v[146:147], v0 offset:0x4000
	ds_read_b64_tr_b16 v[148:149], v0 offset:0x4800
	v_mfma_f32_32x32x16_bf16 v[82:97], v[138:141], v[150:153], v[82:97]
	ds_read_b64_tr_b16 v[150:151], v0 offset:0x5000
	ds_read_b64_tr_b16 v[152:153], v0 offset:0x5800
	v_mfma_f32_32x32x16_bf16 v[82:97], v[134:137], v[154:157], v[82:97]
	ds_read_b64_tr_b16 v[154:155], v0 offset:0x6000
	ds_read_b64_tr_b16 v[156:157], v0 offset:0x6800
	v_mfma_f32_32x32x16_bf16 v[82:97], v[130:133], v[158:161], v[82:97]
	ds_read_b64_tr_b16 v[158:159], v0 offset:0x7000
	ds_read_b64_tr_b16 v[160:161], v0 offset:0x7800
	s_waitcnt lgkmcnt(8)
	v_mfma_f32_32x32x16_bf16 v[66:81], v[142:145], v[184:187], v[66:81]
	ds_read_b64_tr_b16 v[184:185], v0 offset:0x4200
	ds_read_b64_tr_b16 v[186:187], v0 offset:0x4a00
	v_mfma_f32_32x32x16_bf16 v[66:81], v[138:141], v[188:191], v[66:81]
	ds_read_b64_tr_b16 v[188:189], v0 offset:0x5200
	ds_read_b64_tr_b16 v[190:191], v0 offset:0x5a00
	v_mfma_f32_32x32x16_bf16 v[66:81], v[134:137], v[192:195], v[66:81]
	ds_read_b64_tr_b16 v[192:193], v0 offset:0x6200
	ds_read_b64_tr_b16 v[194:195], v0 offset:0x6a00
	v_mfma_f32_32x32x16_bf16 v[66:81], v[130:133], v[196:199], v[66:81]
	ds_read_b64_tr_b16 v[196:197], v0 offset:0x7200
	ds_read_b64_tr_b16 v[198:199], v0 offset:0x7a00
	s_waitcnt lgkmcnt(8)
	v_mfma_f32_32x32x16_bf16 v[50:65], v[142:145], v[146:149], v[50:65]
	ds_read_b64_tr_b16 v[146:147], v0 offset:0x4400
	ds_read_b64_tr_b16 v[148:149], v0 offset:0x4c00
	v_mfma_f32_32x32x16_bf16 v[50:65], v[138:141], v[150:153], v[50:65]
	ds_read_b64_tr_b16 v[150:151], v0 offset:0x5400
	ds_read_b64_tr_b16 v[152:153], v0 offset:0x5c00
	v_mfma_f32_32x32x16_bf16 v[50:65], v[134:137], v[154:157], v[50:65]
	ds_read_b64_tr_b16 v[154:155], v0 offset:0x6400
	ds_read_b64_tr_b16 v[156:157], v0 offset:0x6c00
	v_mfma_f32_32x32x16_bf16 v[50:65], v[130:133], v[158:161], v[50:65]
	ds_read_b64_tr_b16 v[158:159], v0 offset:0x7400
	ds_read_b64_tr_b16 v[160:161], v0 offset:0x7c00
	s_waitcnt lgkmcnt(8)
	v_mfma_f32_32x32x16_bf16 v[34:49], v[142:145], v[184:187], v[34:49]
	ds_read_b64_tr_b16 v[184:185], v0 offset:0x4600
	ds_read_b64_tr_b16 v[186:187], v0 offset:0x4e00
	v_mfma_f32_32x32x16_bf16 v[34:49], v[138:141], v[188:191], v[34:49]
	ds_read_b64_tr_b16 v[188:189], v0 offset:0x5600
	ds_read_b64_tr_b16 v[190:191], v0 offset:0x5e00
	v_mfma_f32_32x32x16_bf16 v[34:49], v[134:137], v[192:195], v[34:49]
	ds_read_b64_tr_b16 v[192:193], v0 offset:0x6600
	ds_read_b64_tr_b16 v[194:195], v0 offset:0x6e00
	v_mfma_f32_32x32x16_bf16 v[34:49], v[130:133], v[196:199], v[34:49]
	ds_read_b64_tr_b16 v[196:197], v0 offset:0x7600
	ds_read_b64_tr_b16 v[198:199], v0 offset:0x7e00
	s_waitcnt lgkmcnt(8)
	s_waitcnt lgkmcnt(0)
	s_waitcnt vmcnt(0)
	s_add_i32 s70, s70, 1
	s_waitcnt lgkmcnt(0)
	s_barrier
	s_add_u32 s48, s48, 0x4000
	s_addc_u32 s49, s49, 0
	v_mfma_f32_32x32x16_bf16 v[18:33], v[142:145], v[146:149], v[18:33]
	v_mfma_f32_32x32x16_bf16 v[2:17], v[142:145], v[184:187], v[2:17]
	v_mfma_f32_32x32x16_bf16 v[18:33], v[138:141], v[150:153], v[18:33]
	v_mfma_f32_32x32x16_bf16 v[2:17], v[138:141], v[188:191], v[2:17]
	v_mfma_f32_32x32x16_bf16 v[18:33], v[134:137], v[154:157], v[18:33]
	v_mfma_f32_32x32x16_bf16 v[2:17], v[134:137], v[192:195], v[2:17]
	s_cmp_eq_u32 s48, 0x1fc000
	v_mfma_f32_32x32x16_bf16 v[18:33], v[130:133], v[158:161], v[18:33]
	v_mfma_f32_32x32x16_bf16 v[2:17], v[130:133], v[196:199], v[2:17]
	s_cbranch_scc1 .LBB0_503
